# rstd_table row dedup with 2 x 164 bytes of padding so that every GEMM loop keeps its previous address modulo 256
# baseline (speedup 1.0000x reference)
.LBB0_581:
	s_nop 0
	s_nop 0
	s_nop 0
	s_nop 0
	s_nop 0
	s_nop 0
	s_nop 0
	s_nop 0
	s_nop 0
	s_nop 0
	s_nop 0
	s_nop 0
	s_nop 0
	s_nop 0
	s_nop 0
	s_nop 0
	s_nop 0
	s_nop 0
	s_nop 0
	s_nop 0
	s_nop 0
	s_nop 0
	s_nop 0
	s_nop 0
	s_nop 0
	s_nop 0
	s_nop 0
	s_nop 0
	s_nop 0
	s_nop 0
	s_nop 0
	s_nop 0
	s_nop 0
	s_nop 0
	s_nop 0
	s_nop 0
	s_nop 0
	s_nop 0
	s_nop 0
	s_nop 0
	s_nop 0
	s_cmp_lt_i32 s80, s94
	s_cselect_b64 s[2:3], -1, 0
	s_cmp_ge_i32 s80, s94
	v_readfirstlane_b32 s18, v166
	s_waitcnt vmcnt(0) lgkmcnt(0)
	s_barrier
	s_cbranch_scc1 .LBB0_583
	s_lshr_b32 s0, s81, 29
	s_add_i32 s0, s80, s0
	s_ashr_i32 s1, s0, 3
	s_and_b32 s0, s0, -8
	s_sub_i32 s0, s80, s0
	s_cmp_lt_i32 s0, 0
	s_cselect_b32 s4, s92, s57
	s_mul_i32 s0, s4, s0
	s_add_i32 s0, s0, s1
	s_abs_i32 s4, s0
	s_mul_hi_u32 s5, s4, s93
	s_mul_i32 s6, s5, s13
	s_sub_i32 s4, s4, s6
	s_ashr_i32 s1, s0, 31
	s_add_i32 s6, s5, 1
	s_sub_i32 s7, s4, s13
	s_cmp_ge_u32 s4, s13
	s_cselect_b32 s5, s6, s5
	s_cselect_b32 s4, s7, s4
	s_add_i32 s6, s5, 1
	s_cmp_ge_u32 s4, s13
	s_cselect_b32 s4, s6, s5
	s_xor_b32 s4, s4, s1
	s_sub_i32 s1, s4, s1
	s_lshl_b32 s4, s1, 3
	s_sub_i32 s5, 0x80, s4
	s_min_i32 s5, s5, 8
	s_abs_i32 s6, s5
	v_cvt_f32_u32_e32 v0, s6
	s_sub_i32 s16, 0, s6
	s_mul_i32 s1, s1, s13
	s_sub_i32 s0, s0, s1
	v_rcp_iflag_f32_e32 v0, v0
	s_abs_i32 s7, s0
	s_xor_b32 s1, s0, s5
	s_ashr_i32 s1, s1, 31
	v_mul_f32_e32 v0, 0x4f7ffffe, v0
	v_cvt_u32_f32_e32 v0, v0
	s_nop 0
	v_readfirstlane_b32 s17, v0
	s_mul_i32 s16, s16, s17
	s_mul_hi_u32 s16, s17, s16
	s_add_i32 s17, s17, s16
	s_mul_hi_u32 s16, s7, s17
	s_mul_i32 s17, s16, s6
	s_sub_i32 s7, s7, s17
	s_add_i32 s17, s16, 1
	s_sub_i32 s19, s7, s6
	s_cmp_ge_u32 s7, s6
	s_cselect_b32 s16, s17, s16
	s_cselect_b32 s7, s19, s7
	s_add_i32 s17, s16, 1
	s_cmp_ge_u32 s7, s6
	s_cselect_b32 s6, s17, s16
	s_xor_b32 s6, s6, s1
	s_sub_i32 s72, s6, s1
	s_mul_i32 s1, s72, s5
	s_sub_i32 s0, s0, s1
	s_add_i32 s0, s0, s4

.LBB0_951:
	s_nop 0
	s_nop 0
	s_nop 0
	s_nop 0
	s_nop 0
	s_nop 0
	s_nop 0
	s_nop 0
	s_nop 0
	s_nop 0
	s_nop 0
	s_nop 0
	s_nop 0
	s_nop 0
	s_nop 0
	s_nop 0
	s_nop 0
	s_nop 0
	s_nop 0
	s_nop 0
	s_nop 0
	s_nop 0
	s_nop 0
	s_nop 0
	s_nop 0
	s_nop 0
	s_nop 0
	s_nop 0
	s_nop 0
	s_nop 0
	s_nop 0
	s_nop 0
	s_nop 0
	s_nop 0
	s_nop 0
	s_nop 0
	s_nop 0
	s_nop 0
	s_nop 0
	s_nop 0
	s_nop 0
	s_cmpk_gt_i32 s80, 0xaff
	v_readfirstlane_b32 s3, v166
	s_waitcnt vmcnt(0) lgkmcnt(0)
	s_barrier
	s_cbranch_scc1 .LBB0_967
	v_lshlrev_b32_e32 v0, 4, v166
	v_add_u32_e32 v2, 0x2000, v0
	v_ashrrev_i32_e32 v3, 31, v2
	v_lshrrev_b32_e32 v3, 22, v3
	v_add_u32_e32 v3, v2, v3
	v_ashrrev_i32_e32 v10, 10, v3
	s_mov_b32 s0, s18
	s_ashr_i32 s5, s3, 6
	v_mul_i32_i24_e32 v3, 0x400, v10
	s_ashr_i32 s4, s3, 8
	s_lshl_b32 s18, s5, 10
	s_mov_b32 s8, s0
	s_and_b32 s0, s0, 1
	v_sub_u32_e32 v2, v2, v3
	s_add_u32 s1, s58, 0x1b800000
	v_lshrrev_b32_e32 v3, 4, v2
	s_addc_u32 s2, s59, 0
	v_bitop3_b32 v2, v3, v2, 32 bitop3:0x6c
	s_cmp_eq_u32 s0, 0
	v_readlane_b32 s6, v254, 21
	v_ashrrev_i32_e32 v3, 31, v2
	v_readlane_b32 s7, v254, 22
	s_cselect_b32 s29, s6, s1
	s_mul_i32 s1, s8, 0xb00000
	v_lshrrev_b32_e32 v3, 26, v3
	s_cselect_b32 s19, s7, s2
	s_mul_hi_u32 s0, s8, 0xb00000
	s_add_u32 s1, s58, s1
	v_add_u32_e32 v3, v2, v3
	v_lshlrev_b32_e32 v4, 3, v10
	s_addc_u32 s0, s59, s0
	v_ashrrev_i32_e32 v11, 6, v3
	v_and_b32_e32 v4, -16, v4
	s_add_u32 s30, s1, 0x100000
	v_add_u32_e32 v4, v11, v4
	s_addc_u32 s31, s0, 0
	v_and_b32_e32 v5, 3, v11
	s_mov_b32 s0, 0x1fffe0
	v_lshrrev_b32_e32 v6, 2, v4
	v_lshlrev_b32_e32 v7, 1, v4
	v_and_b32_e32 v3, 0xc0, v3
	v_and_or_b32 v5, v4, s0, v5
	v_and_b32_e32 v6, 4, v6
	v_and_b32_e32 v7, 24, v7
	v_sub_u32_e32 v2, v2, v3
	v_or3_b32 v5, v5, v6, v7
	v_lshlrev_b32_e32 v6, 5, v10
	v_ashrrev_i16_sdwa v2, v219, sext(v2) dst_sel:DWORD dst_unused:UNUSED_PAD src0_sel:DWORD src1_sel:BYTE_0
	v_and_b32_e32 v6, 32, v6
	v_bfe_i32 v12, v2, 0, 16
	v_add_lshl_u32 v2, v6, v12, 1
	v_lshl_add_u32 v130, v5, 11, v2
	v_lshl_add_u32 v132, v4, 11, v2
	v_bfe_i32 v2, v166, 27, 1
	v_lshrrev_b32_e32 v2, 22, v2
	v_add_u32_e32 v2, v0, v2
	v_and_b32_e32 v2, 0xfffffc00, v2
	v_sub_u32_e32 v0, v0, v2
	v_lshrrev_b32_e32 v2, 4, v0
	v_ashrrev_i32_e32 v3, 31, v166
	v_bitop3_b32 v0, v2, v0, 32 bitop3:0x6c
	v_lshrrev_b32_e32 v3, 26, v3
	v_ashrrev_i32_e32 v2, 31, v0
	v_add_u32_e32 v3, v166, v3
	v_lshrrev_b32_e32 v2, 26, v2
	v_ashrrev_i32_e32 v14, 6, v3
	v_add_u32_e32 v2, v0, v2
	v_lshlrev_b32_e32 v3, 3, v14
	v_ashrrev_i32_e32 v13, 6, v2
	v_and_b32_e32 v3, -16, v3
	v_add_u32_e32 v3, v13, v3
	v_and_b32_e32 v4, 3, v13
	v_and_or_b32 v4, v3, s0, v4
	s_lshr_b32 s0, s81, 29
	s_add_i32 s0, s80, s0
	s_ashr_i32 s1, s0, 3
	s_and_b32 s0, s0, -8
	s_sub_i32 s0, s80, s0
	s_cmp_lt_i32 s0, 0
	s_movk_i32 s2, 0x161
	s_cselect_b32 s2, s2, 0x160
	s_mul_i32 s0, s0, s2
	s_add_i32 s0, s0, s1
	s_mul_hi_i32 s1, s0, 0x2e8ba2e9
	s_lshr_b32 s2, s1, 31
	s_ashr_i32 s1, s1, 5
	s_add_i32 s1, s1, s2
	s_lshl_b32 s6, s1, 3
	s_mulk_i32 s1, 0xb0
	s_sub_i32 s0, s0, s1
	s_bfe_u32 s1, s0, 0x3001c
	s_add_i32 s1, s0, s1
	s_sext_i32_i16 s2, s1
	s_and_b32 s1, s1, 0xfff8
	s_sub_i32 s0, s0, s1
	s_sext_i32_i16 s0, s0
	v_lshrrev_b32_e32 v5, 2, v3
	v_lshlrev_b32_e32 v6, 1, v3
	v_and_b32_e32 v2, 0xc0, v2
	s_lshr_b32 s2, s2, 3
	s_add_i32 s8, s6, s0
	v_and_b32_e32 v5, 4, v5
	v_and_b32_e32 v6, 24, v6
	v_sub_u32_e32 v0, v0, v2
	s_ashr_i32 s9, s8, 31
	s_bfe_i64 s[6:7], s[2:3], 0x100000
	v_or3_b32 v4, v4, v5, v6
	v_lshlrev_b32_e32 v5, 5, v14
	v_ashrrev_i16_sdwa v0, v219, sext(v0) dst_sel:DWORD dst_unused:UNUSED_PAD src0_sel:DWORD src1_sel:BYTE_0
	s_lshl_b64 s[0:1], s[8:9], 19
	s_lshl_b64 s[6:7], s[6:7], 19
	v_and_b32_e32 v5, 32, v5
	v_bfe_i32 v15, v0, 0, 16
	s_add_u32 s20, s30, s6
	v_add_lshl_u32 v2, v5, v15, 1
	s_addc_u32 s21, s31, s7
	s_add_i32 s34, s18, 0
	v_lshl_add_u32 v0, v4, 11, v2
	s_add_i32 m0, s34, 0x10000
	v_lshl_add_u32 v134, v3, 11, v2
	global_load_lds_dwordx4 v0, s[20:21]
	s_add_i32 m0, s34, 0x12000
	s_add_u32 s6, s20, 0x40000
	global_load_lds_dwordx4 v130, s[20:21]
	s_addc_u32 s7, s21, 0
	s_add_i32 m0, s34, 0x14000
	v_mov_b32_e32 v131, v1
	global_load_lds_dwordx4 v0, s[6:7]
	s_add_i32 m0, s34, 0x16000
	s_add_u32 s24, s29, s0
	s_addc_u32 s25, s19, s1
	s_add_i32 s35, s34, 0x2000
	global_load_lds_dwordx4 v130, s[6:7]
	s_mov_b32 m0, s34
	s_add_u32 s0, s24, 0x40000
	global_load_lds_dwordx4 v134, s[24:25]
	s_mov_b32 m0, s35
	s_addc_u32 s1, s25, 0
	s_add_i32 s38, s34, 0x4000
	global_load_lds_dwordx4 v132, s[24:25]
	s_mov_b32 m0, s38
	s_add_i32 s39, s34, 0x6000
	global_load_lds_dwordx4 v134, s[0:1]
	s_mov_b32 m0, s39
	v_mov_b32_e32 v135, v1
	global_load_lds_dwordx4 v132, s[0:1]
	v_mov_b32_e32 v133, v1
	s_cmp_eq_u32 s4, 1
	s_mov_b32 s75, s64
	v_lshl_add_u64 v[8:9], s[20:21], 0, v[0:1]
	v_lshl_add_u64 v[6:7], s[20:21], 0, v[130:131]
	v_lshl_add_u64 v[2:3], s[24:25], 0, v[134:135]
	s_cselect_b64 s[0:1], -1, 0
	v_lshl_add_u64 v[4:5], s[24:25], 0, v[132:133]
	s_mov_b32 s101, s4
	s_lshl_b32 s5, s5, 5
	s_and_b32 s11, s5, 0x60
	s_add_i32 m0, s34, 0x18000
	v_lshl_add_u64 v[8:9], v[8:9], 0, s[22:23]
	s_lshl_b32 s10, s4, 13
	s_lshl_b32 s5, s11, 7
	global_load_lds_dwordx4 v[8:9], off
	v_lshl_add_u64 v[6:7], v[6:7], 0, s[22:23]
	s_add_i32 m0, s34, 0x1a000
	s_add_i32 s57, s34, 0x8000
	s_add_i32 s61, s34, 0xa000
	global_load_lds_dwordx4 v[6:7], off
	v_lshl_add_u64 v[2:3], v[2:3], 0, s[22:23]
	s_mov_b32 m0, s57
	s_add_u32 s6, s20, 0x40080
	global_load_lds_dwordx4 v[2:3], off
	v_lshl_add_u64 v[2:3], v[4:5], 0, s[22:23]
	s_mov_b32 m0, s61
	s_addc_u32 s7, s21, 0
	global_load_lds_dwordx4 v[2:3], off
	s_add_i32 m0, s34, 0x1c000
	v_lshl_add_u64 v[2:3], s[6:7], 0, v[0:1]
	global_load_lds_dwordx4 v[2:3], off
	v_lshl_add_u64 v[2:3], s[6:7], 0, v[130:131]
	s_add_i32 m0, s34, 0x1e000
	v_lshlrev_b32_e32 v6, 2, v166
	global_load_lds_dwordx4 v[2:3], off
	s_cmp_lg_u32 s101, 1
	s_cbranch_scc1 .LBB0_954
	s_barrier
